# scan compute loop: the 12-state pad before the vn conversion replaced by 12 independent state-scaling multiplies
# speedup vs baseline: 1.0104x; 1.0104x over previous
; #define LAS __attribute__((address_space(3)))
; #define PACK8(v, base) pack8f((v)[(base) + 0], (v)[(base) + 1], (v)[(base) + 2], (v)[(base) + 3], (v)[(base) + 4], (v)[(base) + 5], (v)[(base) + 6], (v)[(base) + 7])
; #define SBAR() __builtin_amdgcn_sched_barrier(0)
; #define LOAD_WQ(f, g) do { _Pragma("unroll") for (int e = 0; e < 2; ++e) { f[4 * e] = LDF((2 * (g) + e) * 1024); f[4 * e + 1] = LDF((8 + 2 * (g) + e) * 1024); \
;                 f[4 * e + 2] = LDF(16384 + (2 * (g) + e) * 1024); f[4 * e + 3] = LDF(16384 + (8 + 2 * (g) + e) * 1024); } } while (0)
; #define COMP_WQ(f, g) do { _Pragma("unroll") for (int e = 0; e < 2; ++e) { const bf16x8 sb = PACK8(S[(2 * (g) + e) >> 1], ((2 * (g) + e) & 1) * 8); \
;                 vn[0] = MFMA32(f[4 * e], sb, vn[0]); vn[1] = MFMA32(f[4 * e + 1], sb, vn[1]); o[0] = MFMA32(f[4 * e + 2], sb, o[0]); o[1] = MFMA32(f[4 * e + 3], sb, o[1]); } } while (0)
; DI void gdn_scan(const Args& a, int l, int bh, LAS unsigned char* lds, const int tidx, const bool nostore) {
;     ...
;             const LAS unsigned char* buf = lds + (n & 1) * REC_BYTES + lane * 16;
;             bf16x8 fa[8], fb[8];
;     ...
;             LOAD_WQ(fa, 0); SBAR(); LOAD_WQ(fb, 1); SBAR();
;             COMP_WQ(fa, 0); SBAR(); LOAD_WQ(fa, 2); SBAR();
;             COMP_WQ(fb, 1); SBAR(); LOAD_WQ(fb, 3); SBAR();
;             COMP_WQ(fa, 2); SBAR();
; #pragma unroll
;             for (int e = 0; e < 8; ++e) fa[e] = LDF(49152 + e * 1024);
;             SBAR();
;             COMP_WQ(fb, 3); SBAR();
; #pragma unroll
;             for (int e = 0; e < 8; ++e) fb[e] = LDF(32768 + e * 1024);
;             SBAR();
;             bf16x8 Vb[4];
; #pragma unroll
;             for (int s2 = 0; s2 < 4; ++s2) Vb[s2] = PACK8(vn[s2 >> 1], (s2 & 1) * 8);
.Lscan_top_done:
	s_and_b32 s5, s4, 1
	s_mul_i32 s6, s5, 0xe000
	v_add_u32_e32 v204, s6, v150
	ds_read_b128 v[152:155], v204
	ds_read_b128 v[156:159], v204 offset:8192
	ds_read_b128 v[64:67], v204 offset:16384
	ds_read_b128 v[68:71], v204 offset:24576
	ds_read_b128 v[160:163], v204 offset:1024
	ds_read_b128 v[164:167], v204 offset:9216
	ds_read_b128 v[168:171], v204 offset:17408
	ds_read_b128 v[172:175], v204 offset:25600
	ds_read_b128 v[176:179], v204 offset:2048
	ds_read_b128 v[180:183], v204 offset:3072
	ds_read_b128 v[184:187], v204 offset:10240
	ds_read_b128 v[188:191], v204 offset:11264
	ds_read_b128 v[192:195], v204 offset:18432
	ds_read_b128 v[196:199], v204 offset:19456
	ds_read_b128 v[200:203], v204 offset:26624
	ds_read_b128 v[222:225], v204 offset:27648
	v_cvt_pk_bf16_f32 v226, v48, v49
	v_cvt_pk_bf16_f32 v227, v50, v51
	v_cvt_pk_bf16_f32 v228, v52, v53
	v_cvt_pk_bf16_f32 v229, v54, v55
	v_cvt_pk_bf16_f32 v230, v56, v57
	v_cvt_pk_bf16_f32 v231, v58, v59
	s_waitcnt lgkmcnt(13)
	v_mfma_f32_32x32x16_bf16 v[80:95], v[64:67], v[226:229], 0
	v_cvt_pk_bf16_f32 v232, v60, v61
	v_cvt_pk_bf16_f32 v233, v62, v63
	s_waitcnt lgkmcnt(12)
	v_mfma_f32_32x32x16_bf16 v[64:79], v[68:71], v[226:229], 0
	s_waitcnt lgkmcnt(9)
	v_mfma_f32_32x32x16_bf16 v[80:95], v[168:171], v[230:233], v[80:95]
	s_waitcnt lgkmcnt(8)
	v_mfma_f32_32x32x16_bf16 v[64:79], v[172:175], v[230:233], v[64:79]
	v_mfma_f32_32x32x16_bf16 v[112:127], v[152:155], v[226:229], v[112:127]
	v_mfma_f32_32x32x16_bf16 v[96:111], v[156:159], v[226:229], v[96:111]
	v_mfma_f32_32x32x16_bf16 v[112:127], v[160:163], v[230:233], v[112:127]
	ds_read_b128 v[152:155], v204 offset:4096
	ds_read_b128 v[156:159], v204 offset:5120
	ds_read_b128 v[160:163], v204 offset:12288
	ds_read_b128 v[168:171], v204 offset:13312
	ds_read_b128 v[172:175], v204 offset:20480
	ds_read_b128 v[226:229], v204 offset:21504
	ds_read_b128 v[234:237], v204 offset:28672
	ds_read_b128 v[248:251], v204 offset:29696
	v_mfma_f32_32x32x16_bf16 v[96:111], v[164:167], v[230:233], v[96:111]
	v_cvt_pk_bf16_f32 v164, v32, v33
	v_cvt_pk_bf16_f32 v165, v34, v35
	v_cvt_pk_bf16_f32 v166, v36, v37
	v_cvt_pk_bf16_f32 v167, v38, v39
	s_waitcnt lgkmcnt(11)
	s_nop 0
	v_mfma_f32_32x32x16_bf16 v[80:95], v[192:195], v[164:167], v[80:95]
	v_cvt_pk_bf16_f32 v192, v40, v41
	v_cvt_pk_bf16_f32 v193, v42, v43
	v_cvt_pk_bf16_f32 v194, v44, v45
	v_cvt_pk_bf16_f32 v195, v46, v47
	s_waitcnt lgkmcnt(9)
	v_mfma_f32_32x32x16_bf16 v[64:79], v[200:203], v[164:167], v[64:79]
	v_mfma_f32_32x32x16_bf16 v[80:95], v[196:199], v[192:195], v[80:95]
	s_waitcnt lgkmcnt(8)
	v_mfma_f32_32x32x16_bf16 v[64:79], v[222:225], v[192:195], v[64:79]
	v_mfma_f32_32x32x16_bf16 v[112:127], v[176:179], v[164:167], v[112:127]
	v_mfma_f32_32x32x16_bf16 v[96:111], v[184:187], v[164:167], v[96:111]
	v_mfma_f32_32x32x16_bf16 v[112:127], v[180:183], v[192:195], v[112:127]
	ds_read_b128 v[164:167], v204 offset:6144
	ds_read_b128 v[176:179], v204 offset:7168
	ds_read_b128 v[180:183], v204 offset:14336
	ds_read_b128 v[184:187], v204 offset:15360
	ds_read_b128 v[196:199], v204 offset:22528
	ds_read_b128 v[200:203], v204 offset:23552
	ds_read_b128 v[222:225], v204 offset:30720
	ds_read_b128 v[230:233], v204 offset:31744
	v_mfma_f32_32x32x16_bf16 v[96:111], v[188:191], v[192:195], v[96:111]
	v_cvt_pk_bf16_f32 v188, v16, v17
	v_cvt_pk_bf16_f32 v189, v18, v19
	v_cvt_pk_bf16_f32 v190, v20, v21
	v_cvt_pk_bf16_f32 v191, v22, v23
	s_waitcnt lgkmcnt(11)
	s_nop 0
	v_mfma_f32_32x32x16_bf16 v[80:95], v[172:175], v[188:191], v[80:95]
	v_cvt_pk_bf16_f32 v172, v24, v25
	v_cvt_pk_bf16_f32 v173, v26, v27
	v_cvt_pk_bf16_f32 v174, v28, v29
	v_cvt_pk_bf16_f32 v175, v30, v31
	s_waitcnt lgkmcnt(9)
	v_mfma_f32_32x32x16_bf16 v[64:79], v[234:237], v[188:191], v[64:79]
	v_mfma_f32_32x32x16_bf16 v[80:95], v[226:229], v[172:175], v[80:95]
	s_waitcnt lgkmcnt(8)
	v_mfma_f32_32x32x16_bf16 v[64:79], v[248:251], v[172:175], v[64:79]
	v_mfma_f32_32x32x16_bf16 v[112:127], v[152:155], v[188:191], v[112:127]
	v_mfma_f32_32x32x16_bf16 v[96:111], v[160:163], v[188:191], v[96:111]
	v_mfma_f32_32x32x16_bf16 v[112:127], v[156:159], v[172:175], v[112:127]
	ds_read_b128 v[152:155], v204 offset:49152
	ds_read_b128 v[156:159], v204 offset:50176
	ds_read_b128 v[160:163], v204 offset:51200
	ds_read_b128 v[188:191], v204 offset:52224
	ds_read_b128 v[192:195], v204 offset:53248
	ds_read_b128 v[226:229], v204 offset:54272
	ds_read_b128 v[234:237], v204 offset:55296
	ds_read_b128 v[248:251], v204 offset:56320
	v_mfma_f32_32x32x16_bf16 v[96:111], v[168:171], v[172:175], v[96:111]
	v_cvt_pk_bf16_f32 v168, v0, v1
	v_cvt_pk_bf16_f32 v169, v2, v3
	v_cvt_pk_bf16_f32 v170, v4, v5
	v_cvt_pk_bf16_f32 v171, v6, v7
	v_cvt_pk_bf16_f32 v172, v8, v9
	v_cvt_pk_bf16_f32 v173, v10, v11
	s_waitcnt lgkmcnt(13)
	v_mfma_f32_32x32x16_bf16 v[96:111], v[180:183], v[168:171], v[96:111]
	v_cvt_pk_bf16_f32 v174, v12, v13
	v_cvt_pk_bf16_f32 v175, v14, v15
	s_waitcnt lgkmcnt(11)
	v_mfma_f32_32x32x16_bf16 v[80:95], v[196:199], v[168:171], v[80:95]
	s_waitcnt lgkmcnt(9)
	v_mfma_f32_32x32x16_bf16 v[64:79], v[222:225], v[168:171], v[64:79]
	v_mfma_f32_32x32x16_bf16 v[96:111], v[184:187], v[172:175], v[96:111]
	v_mfma_f32_32x32x16_bf16 v[80:95], v[200:203], v[172:175], v[80:95]
	s_waitcnt lgkmcnt(8)
; #define MFMA32(a, b, c) __builtin_amdgcn_mfma_f32_32x32x16_bf16((a), (b), (c), 0, 0, 0)
; #define PACK8(v, base) pack8f((v)[(base) + 0], (v)[(base) + 1], (v)[(base) + 2], (v)[(base) + 3], (v)[(base) + 4], (v)[(base) + 5], (v)[(base) + 6], (v)[(base) + 7])
; #define SBAR() __builtin_amdgcn_sched_barrier(0)
; DI void gdn_scan(const Args& a, int l, int bh, LAS unsigned char* lds, const int tidx, const bool nostore) {
;     ...
;             bf16x8 Vb[4];
; #pragma unroll
;             for (int s2 = 0; s2 < 4; ++s2) Vb[s2] = PACK8(vn[s2 >> 1], (s2 & 1) * 8);
; #pragma unroll
;             for (int s2 = 0; s2 < 4; ++s2)
; #pragma unroll
;                 for (int mt = 0; mt < 2; ++mt) o[mt] = MFMA32(fa[mt * 4 + s2], Vb[s2], o[mt]);
;             SBAR();
; #pragma unroll
;             for (int e = 0; e < 8; ++e) fa[e] = LDF(32768 + 8192 + e * 1024);
;             SBAR();
; #pragma unroll
;             for (int t = 0; t < 4; ++t)
; #pragma unroll
;                 for (int r = 0; r < 16; ++r) S[t][r] *= eg;
; #pragma unroll
;             for (int s2 = 0; s2 < 4; ++s2)
; #pragma unroll
;                 for (int t = 0; t < 2; ++t) S[t] = MFMA32(fb[t * 4 + s2], Vb[s2], S[t]);
;             SBAR();
; #pragma unroll
;             for (int s2 = 0; s2 < 4; ++s2)
; #pragma unroll
;                 for (int t = 2; t < 4; ++t) S[t] = MFMA32(fa[(t - 2) * 4 + s2], Vb[s2], S[t]);
	v_mfma_f32_32x32x16_bf16 v[64:79], v[230:233], v[172:175], v[64:79]
	v_mfma_f32_32x32x16_bf16 v[112:127], v[164:167], v[168:171], v[112:127]
	ds_read_b128 v[164:167], v204 offset:32768
	ds_read_b128 v[168:171], v204 offset:33792
	ds_read_b128 v[180:183], v204 offset:34816
	ds_read_b128 v[184:187], v204 offset:35840
	ds_read_b128 v[196:199], v204 offset:36864
	ds_read_b128 v[200:203], v204 offset:37888
	ds_read_b128 v[222:225], v204 offset:38912
	ds_read_b128 v[230:233], v204 offset:39936
	v_mfma_f32_32x32x16_bf16 v[112:127], v[176:179], v[172:175], v[112:127]
	v_mul_f32_e32 v62, v148, v62
	v_mul_f32_e32 v63, v148, v63
	v_mul_f32_e32 v60, v148, v60
	v_mul_f32_e32 v61, v148, v61
	v_mul_f32_e32 v58, v148, v58
	v_mul_f32_e32 v59, v148, v59
	v_mul_f32_e32 v56, v148, v56
	v_mul_f32_e32 v57, v148, v57
	v_mul_f32_e32 v54, v148, v54
	v_mul_f32_e32 v55, v148, v55
	v_mul_f32_e32 v52, v148, v52
	v_mul_f32_e32 v53, v148, v53
	v_cvt_pk_bf16_f32 v112, v112, v113
	v_cvt_pk_bf16_f32 v113, v114, v115
	v_cvt_pk_bf16_f32 v114, v116, v117
	v_cvt_pk_bf16_f32 v115, v118, v119
	v_cvt_pk_bf16_f32 v116, v120, v121
	v_cvt_pk_bf16_f32 v117, v122, v123
	s_waitcnt lgkmcnt(14)
	v_mfma_f32_32x32x16_bf16 v[80:95], v[152:155], v[112:115], v[80:95]
	v_cvt_pk_bf16_f32 v118, v124, v125
	v_cvt_pk_bf16_f32 v119, v126, v127
	v_cvt_pk_bf16_f32 v96, v96, v97
	v_cvt_pk_bf16_f32 v97, v98, v99
	v_cvt_pk_bf16_f32 v98, v100, v101
	v_cvt_pk_bf16_f32 v99, v102, v103
	v_cvt_pk_bf16_f32 v100, v104, v105
	s_waitcnt lgkmcnt(11)
	v_mfma_f32_32x32x16_bf16 v[64:79], v[192:195], v[112:115], v[64:79]
	v_cvt_pk_bf16_f32 v101, v106, v107
	v_cvt_pk_bf16_f32 v102, v108, v109
	v_cvt_pk_bf16_f32 v103, v110, v111
	v_mfma_f32_32x32x16_bf16 v[80:95], v[156:159], v[116:119], v[80:95]
	s_waitcnt lgkmcnt(10)
	v_mfma_f32_32x32x16_bf16 v[64:79], v[226:229], v[116:119], v[64:79]
	v_mfma_f32_32x32x16_bf16 v[80:95], v[160:163], v[96:99], v[80:95]
	s_waitcnt lgkmcnt(9)
	v_mfma_f32_32x32x16_bf16 v[64:79], v[234:237], v[96:99], v[64:79]
	v_mfma_f32_32x32x16_bf16 v[80:95], v[188:191], v[100:103], v[80:95]
	s_waitcnt lgkmcnt(8)
	v_mfma_f32_32x32x16_bf16 v[64:79], v[248:251], v[100:103], v[64:79]
	ds_read_b128 v[104:107], v204 offset:40960
	ds_read_b128 v[108:111], v204 offset:41984
	ds_read_b128 v[120:123], v204 offset:43008
	ds_read_b128 v[124:127], v204 offset:44032
	ds_read_b128 v[152:155], v204 offset:45056
	ds_read_b128 v[156:159], v204 offset:46080
	ds_read_b128 v[160:163], v204 offset:47104
	ds_read_b128 v[172:175], v204 offset:48128
	s_nop 0
	v_mul_f32_e32 v50, v148, v50
	v_mul_f32_e32 v51, v148, v51
	v_mul_f32_e32 v48, v148, v48
	v_mul_f32_e32 v49, v148, v49
	v_mul_f32_e32 v46, v148, v46
	v_mul_f32_e32 v47, v148, v47
	v_mul_f32_e32 v44, v148, v44
	v_mul_f32_e32 v45, v148, v45
	v_mul_f32_e32 v42, v148, v42
	v_mul_f32_e32 v43, v148, v43
	v_mul_f32_e32 v40, v148, v40
	v_mul_f32_e32 v41, v148, v41
	v_mul_f32_e32 v38, v148, v38
	v_mul_f32_e32 v39, v148, v39
	v_mul_f32_e32 v36, v148, v36
	v_mul_f32_e32 v37, v148, v37
	v_mul_f32_e32 v34, v148, v34
	v_mul_f32_e32 v35, v148, v35
	v_mul_f32_e32 v32, v148, v32
	v_mul_f32_e32 v33, v148, v33
	s_waitcnt lgkmcnt(14)
	v_mfma_f32_32x32x16_bf16 v[48:63], v[164:167], v[112:115], v[48:63]
	v_mul_f32_e64 v30, v30, v148
	v_mul_f32_e64 v31, v31, v148
	v_mul_f32_e64 v28, v28, v148
	v_mul_f32_e64 v29, v29, v148
	v_mul_f32_e64 v26, v26, v148
	v_mul_f32_e64 v27, v27, v148
	v_mul_f32_e32 v24, v148, v24
	v_mul_f32_e32 v25, v148, v25
	v_mul_f32_e32 v22, v148, v22
	v_mul_f32_e32 v23, v148, v23
	v_mul_f32_e32 v20, v148, v20
	v_mul_f32_e32 v21, v148, v21
	v_mul_f32_e32 v18, v148, v18
	v_mul_f32_e32 v19, v148, v19
	s_waitcnt lgkmcnt(11)
	v_mfma_f32_32x32x16_bf16 v[32:47], v[196:199], v[112:115], v[32:47]
	v_mul_f32_e64 v16, v16, v148
	v_mul_f32_e64 v17, v17, v148
	v_mul_f32_e64 v14, v14, v148
	v_mul_f32_e64 v15, v15, v148
	v_mul_f32_e64 v12, v12, v148
	v_mul_f32_e64 v13, v13, v148
	v_mul_f32_e32 v10, v148, v10
	v_mul_f32_e32 v11, v148, v11
	v_mul_f32_e32 v8, v148, v8
	v_mul_f32_e32 v9, v148, v9
	v_mul_f32_e32 v6, v148, v6
	v_mul_f32_e32 v7, v148, v7
	v_mul_f32_e32 v4, v148, v4
	v_mul_f32_e32 v5, v148, v5
	v_mfma_f32_32x32x16_bf16 v[48:63], v[168:171], v[116:119], v[48:63]
	v_mul_f32_e64 v2, v2, v148
	v_mul_f32_e64 v3, v3, v148
	v_mul_f32_e64 v0, v0, v148
	v_mul_f32_e64 v1, v1, v148
	s_waitcnt lgkmcnt(10)
	v_mfma_f32_32x32x16_bf16 v[32:47], v[200:203], v[116:119], v[32:47]
	v_mfma_f32_32x32x16_bf16 v[48:63], v[180:183], v[96:99], v[48:63]
	s_waitcnt lgkmcnt(9)
	v_mfma_f32_32x32x16_bf16 v[32:47], v[222:225], v[96:99], v[32:47]
	v_mfma_f32_32x32x16_bf16 v[48:63], v[184:187], v[100:103], v[48:63]
	s_waitcnt lgkmcnt(8)
	v_mfma_f32_32x32x16_bf16 v[32:47], v[230:233], v[100:103], v[32:47]
	s_waitcnt lgkmcnt(7)
	v_mfma_f32_32x32x16_bf16 v[16:31], v[104:107], v[112:115], v[16:31]
	s_mulk_i32 s5, 0x4400
	v_cvt_pk_bf16_f32 v80, v80, v81
	v_cvt_pk_bf16_f32 v81, v82, v83
	v_cvt_pk_bf16_f32 v64, v64, v65
	v_cvt_pk_bf16_f32 v65, v66, v67
	s_add_i32 s4, s4, 1
	s_add_u32 s0, s0, 4
	s_waitcnt lgkmcnt(3)
	v_mfma_f32_32x32x16_bf16 v[0:15], v[152:155], v[112:115], v[0:15]
	s_addc_u32 s1, s1, 0
	v_lshl_add_u64 v[144:145], v[144:145], 0, s[10:11]
	v_lshl_add_u64 v[146:147], v[146:147], 0, s[10:11]
	s_cmp_eq_u32 s4, 63
	s_nop 0
	s_nop 0
	v_mfma_f32_32x32x16_bf16 v[16:31], v[108:111], v[116:119], v[16:31]
	s_waitcnt lgkmcnt(2)
	v_mfma_f32_32x32x16_bf16 v[0:15], v[156:159], v[116:119], v[0:15]
	v_mfma_f32_32x32x16_bf16 v[16:31], v[120:123], v[96:99], v[16:31]
	s_waitcnt lgkmcnt(1)
; #define LAS __attribute__((address_space(3)))
; DI unsigned pk2(float lo, float hi) { const f32x2_t v = {lo, hi}; return __builtin_bit_cast(unsigned, __builtin_convertvector(v, bf16x2_t)); }
; DI void gdn_scan(const Args& a, int l, int bh, LAS unsigned char* lds, const int tidx, const bool nostore) {
;     ...
;             for (int mt = 0; mt < 2; ++mt) {
; #pragma unroll
;                 for (int g8 = 0; g8 < 2; ++g8) { const u32x4 u = un[mt][g8];
;                     vn[mt][8 * g8] = bflo(u.x); vn[mt][8 * g8 + 1] = bfhi(u.x); vn[mt][8 * g8 + 2] = bflo(u.y); vn[mt][8 * g8 + 3] = bfhi(u.y);
;                     vn[mt][8 * g8 + 4] = bflo(u.z); vn[mt][8 * g8 + 5] = bfhi(u.z); vn[mt][8 * g8 + 6] = bflo(u.w); vn[mt][8 * g8 + 7] = bfhi(u.w); }
; #pragma unroll
;                 for (int r = 0; r < 16; ++r) o[mt][r] = 0.f; }
;             if (n < 63) {
; #pragma unroll
;                 for (int mt = 0; mt < 2; ++mt) { const u32x4* up = (const u32x4*)(urec + (size_t)(n + 1) * 16384) + ((size_t)((wave * 2 + mt) * 64 + lane)) * 2; un[mt][0] = up[0]; un[mt][1] = up[1]; }
;                 egn = egl[n + 1];
;             }
;             const LAS unsigned char* buf = lds + (n & 1) * REC_BYTES + lane * 16;
;             bf16x8 fa[8], fb[8];
;     ...
;             LOAD_WQ(fa, 0); SBAR(); LOAD_WQ(fb, 1); SBAR();
;             COMP_WQ(fa, 0); SBAR(); LOAD_WQ(fa, 2); SBAR();
;     ...
;             for (int s2 = 0; s2 < 4; ++s2)
; #pragma unroll
;                 for (int t = 0; t < 2; ++t) S[t] = MFMA32(fb[t * 4 + s2], Vb[s2], S[t]);
;             SBAR();
; #pragma unroll
;             for (int s2 = 0; s2 < 4; ++s2)
; #pragma unroll
;                 for (int t = 2; t < 4; ++t) S[t] = MFMA32(fa[(t - 2) * 4 + s2], Vb[s2], S[t]);
;     ...
;             LAS bf16_t* ost = (LAS bf16_t*)(lds + SCAN_OST + (n & 1) * OST_BYTES) + (4 * hf) * OST_PITCH + wave * 32 + (lane & 31);
; #pragma unroll
;             for (int mt = 0; mt < 2; ++mt)
; #pragma unroll
;                 for (int i = 0; i < 4; ++i) { const unsigned w0 = pk2(o[mt][4 * i], o[mt][4 * i + 1]), w1 = pk2(o[mt][4 * i + 2], o[mt][4 * i + 3]);
;                     LAS bf16_t* d = ost + (mt * 32 + 8 * i) * OST_PITCH;
;                     d[0] = (bf16_t)(w0 & 0xffffu); d[OST_PITCH] = (bf16_t)(w0 >> 16); d[2 * OST_PITCH] = (bf16_t)(w1 & 0xffffu); d[3 * OST_PITCH] = (bf16_t)(w1 >> 16); }
;             LDSBAR();
	v_mfma_f32_32x32x16_bf16 v[0:15], v[160:163], v[96:99], v[0:15]
	v_add_u32_e32 v96, s5, v149
	ds_write_b16 v96, v80
	ds_write_b16_d16_hi v96, v80 offset:272
	ds_write_b16 v96, v81 offset:544
	ds_write_b16_d16_hi v96, v81 offset:816
	v_cvt_pk_bf16_f32 v80, v84, v85
	v_cvt_pk_bf16_f32 v81, v86, v87
	ds_write_b16 v96, v80 offset:2176
	ds_write_b16_d16_hi v96, v80 offset:2448
	ds_write_b16 v96, v81 offset:2720
	ds_write_b16_d16_hi v96, v81 offset:2992
	v_cvt_pk_bf16_f32 v80, v88, v89
	v_cvt_pk_bf16_f32 v81, v90, v91
	v_mfma_f32_32x32x16_bf16 v[16:31], v[124:127], v[100:103], v[16:31]
	ds_write_b16 v96, v80 offset:4352
	ds_write_b16_d16_hi v96, v80 offset:4624
	ds_write_b16 v96, v81 offset:4896
	ds_write_b16_d16_hi v96, v81 offset:5168
	v_cvt_pk_bf16_f32 v80, v92, v93
	v_cvt_pk_bf16_f32 v81, v94, v95
	ds_write_b16 v96, v80 offset:6528
	ds_write_b16_d16_hi v96, v80 offset:6800
	ds_write_b16 v96, v81 offset:7072
	ds_write_b16_d16_hi v96, v81 offset:7344
	ds_write_b16 v96, v64 offset:8704
	ds_write_b16_d16_hi v96, v64 offset:8976
	ds_write_b16 v96, v65 offset:9248
	ds_write_b16_d16_hi v96, v65 offset:9520
	v_cvt_pk_bf16_f32 v64, v68, v69
	v_cvt_pk_bf16_f32 v65, v70, v71
	s_waitcnt lgkmcnt(14)
	v_mfma_f32_32x32x16_bf16 v[0:15], v[172:175], v[100:103], v[0:15]
	ds_write_b16 v96, v64 offset:10880
	ds_write_b16_d16_hi v96, v64 offset:11152
	ds_write_b16 v96, v65 offset:11424
	ds_write_b16_d16_hi v96, v65 offset:11696
	v_cvt_pk_bf16_f32 v64, v72, v73
	v_cvt_pk_bf16_f32 v65, v74, v75
	ds_write_b16 v96, v64 offset:13056
	ds_write_b16_d16_hi v96, v64 offset:13328
	ds_write_b16 v96, v65 offset:13600
	ds_write_b16_d16_hi v96, v65 offset:13872
	v_cvt_pk_bf16_f32 v64, v76, v77
	v_cvt_pk_bf16_f32 v65, v78, v79
	ds_write_b16 v96, v64 offset:15232
	ds_write_b16_d16_hi v96, v64 offset:15504
	ds_write_b16 v96, v65 offset:15776
	ds_write_b16_d16_hi v96, v65 offset:16048
	s_waitcnt lgkmcnt(0)
	s_barrier
	s_cbranch_scc0 .LBB0_380
	s_waitcnt vmcnt(5)
	v_add_u32_e32 v96, 0x10000, v150
	v_lshlrev_b32_e32 v80, 16, v132
	v_and_b32_e32 v81, 0xffff0000, v132
	v_lshlrev_b32_e32 v82, 16, v133
	v_and_b32_e32 v83, 0xffff0000, v133
	v_lshlrev_b32_e32 v84, 16, v134
	v_and_b32_e32 v85, 0xffff0000, v134
	v_lshlrev_b32_e32 v86, 16, v135
	v_and_b32_e32 v87, 0xffff0000, v135
	v_lshlrev_b32_e32 v88, 16, v128
	v_and_b32_e32 v89, 0xffff0000, v128
	v_lshlrev_b32_e32 v90, 16, v129
	v_and_b32_e32 v91, 0xffff0000, v129
	v_lshlrev_b32_e32 v92, 16, v130
	v_and_b32_e32 v93, 0xffff0000, v130
	v_lshlrev_b32_e32 v94, 16, v131
	v_and_b32_e32 v95, 0xffff0000, v131
	ds_read_b128 v[128:131], v150 offset:57344
	ds_read_b128 v[132:135], v96
	v_add_u32_e32 v96, 0x12000, v150
	v_add_u32_e32 v100, 0x14000, v150
	v_add_u32_e32 v104, 0x10400, v150
	v_and_b32_e32 v79, 0xffff0000, v139
	v_lshlrev_b32_e32 v64, 16, v140
	v_and_b32_e32 v65, 0xffff0000, v140
	v_lshlrev_b32_e32 v66, 16, v141
	v_and_b32_e32 v67, 0xffff0000, v141
	v_lshlrev_b32_e32 v68, 16, v142
	v_and_b32_e32 v69, 0xffff0000, v142
	v_lshlrev_b32_e32 v70, 16, v143
	v_and_b32_e32 v71, 0xffff0000, v143
	v_lshlrev_b32_e32 v72, 16, v136
	v_and_b32_e32 v73, 0xffff0000, v136
	v_lshlrev_b32_e32 v74, 16, v137
	v_and_b32_e32 v75, 0xffff0000, v137
	v_lshlrev_b32_e32 v76, 16, v138
	v_and_b32_e32 v77, 0xffff0000, v138
	v_lshlrev_b32_e32 v78, 16, v139
	ds_read_b128 v[96:99], v96
	ds_read_b128 v[100:103], v100
	ds_read_b128 v[136:139], v150 offset:58368
	ds_read_b128 v[140:143], v104
	v_add_u32_e32 v104, 0x12400, v150
	ds_read_b128 v[144:147], v104
	v_add_u32_e32 v104, 0x14400, v150
	ds_read_b128 v[152:155], v104
	v_add_u32_e32 v104, 0x10800, v150
	v_add_u32_e32 v105, 0x12800, v150
	ds_read_b128 v[156:159], v104
	ds_read_b128 v[160:163], v105
	v_add_u32_e32 v104, 0x14800, v150
	ds_read_b128 v[164:167], v150 offset:59392
	ds_read_b128 v[168:171], v150 offset:60416
	v_add_u32_e32 v105, 0x10c00, v150
	ds_read_b128 v[172:175], v104
	ds_read_b128 v[176:179], v105
	v_add_u32_e32 v104, 0x12c00, v150
	v_add_u32_e32 v105, 0x14c00, v150
	ds_read_b128 v[180:183], v104
	ds_read_b128 v[184:187], v105
	v_cvt_pk_bf16_f32 v48, v48, v49
	v_cvt_pk_bf16_f32 v49, v50, v51
	v_cvt_pk_bf16_f32 v50, v52, v53
	v_cvt_pk_bf16_f32 v51, v54, v55
	v_cvt_pk_bf16_f32 v52, v56, v57
	v_cvt_pk_bf16_f32 v53, v58, v59
	s_waitcnt lgkmcnt(13)
	v_mfma_f32_32x32x16_bf16 v[112:127], v[96:99], v[48:51], 0
	v_cvt_pk_bf16_f32 v54, v60, v61
	v_cvt_pk_bf16_f32 v55, v62, v63
	s_waitcnt lgkmcnt(12)
	v_mfma_f32_32x32x16_bf16 v[96:111], v[100:103], v[48:51], 0
	s_waitcnt lgkmcnt(9)
	v_mfma_f32_32x32x16_bf16 v[112:127], v[144:147], v[52:55], v[112:127]
	s_waitcnt lgkmcnt(8)
	v_mfma_f32_32x32x16_bf16 v[96:111], v[152:155], v[52:55], v[96:111]
	v_mfma_f32_32x32x16_bf16 v[80:95], v[128:131], v[48:51], v[80:95]
	v_add_u32_e32 v56, 0x13000, v150
	v_add_u32_e32 v144, 0x13400, v150
	v_add_u32_e32 v148, 0x15400, v150
	v_mfma_f32_32x32x16_bf16 v[64:79], v[132:135], v[48:51], v[64:79]
	v_add_u32_e32 v48, 0x11000, v150
	v_add_u32_e32 v132, 0x15000, v150
	ds_read_b128 v[48:51], v48
	ds_read_b128 v[56:59], v56
	ds_read_b128 v[60:63], v150 offset:61440
	ds_read_b128 v[128:131], v150 offset:62464
	v_mfma_f32_32x32x16_bf16 v[80:95], v[136:139], v[52:55], v[80:95]
	v_add_u32_e32 v136, 0x11400, v150
	ds_read_b128 v[132:135], v132
	ds_read_b128 v[136:139], v136
	ds_read_b128 v[144:147], v144
	ds_read_b128 v[152:155], v148
	v_mfma_f32_32x32x16_bf16 v[64:79], v[140:143], v[52:55], v[64:79]
	v_cvt_pk_bf16_f32 v32, v32, v33
	v_cvt_pk_bf16_f32 v33, v34, v35
	v_cvt_pk_bf16_f32 v34, v36, v37
	v_cvt_pk_bf16_f32 v35, v38, v39
	v_cvt_pk_bf16_f32 v36, v40, v41
	v_cvt_pk_bf16_f32 v37, v42, v43
	s_waitcnt lgkmcnt(14)
; #define LAS __attribute__((address_space(3)))
; #define MFMA32(a, b, c) __builtin_amdgcn_mfma_f32_32x32x16_bf16((a), (b), (c), 0, 0, 0)
; DI void gdn_scan(const Args& a, int l, int bh, LAS unsigned char* lds, const int tidx, const bool nostore) {
;     ...
;             LOAD_WQ(fa, 0); SBAR(); LOAD_WQ(fb, 1); SBAR();
;             COMP_WQ(fa, 0); SBAR(); LOAD_WQ(fa, 2); SBAR();
;             COMP_WQ(fb, 1); SBAR(); LOAD_WQ(fb, 3); SBAR();
;             COMP_WQ(fa, 2); SBAR();
; #pragma unroll
;             for (int e = 0; e < 8; ++e) fa[e] = LDF(49152 + e * 1024);
;             SBAR();
;             COMP_WQ(fb, 3); SBAR();
; #pragma unroll
;             for (int e = 0; e < 8; ++e) fb[e] = LDF(32768 + e * 1024);
;             SBAR();
;             bf16x8 Vb[4];
; #pragma unroll
;             for (int s2 = 0; s2 < 4; ++s2) Vb[s2] = PACK8(vn[s2 >> 1], (s2 & 1) * 8);
; #pragma unroll
;             for (int s2 = 0; s2 < 4; ++s2)
; #pragma unroll
;                 for (int mt = 0; mt < 2; ++mt) o[mt] = MFMA32(fa[mt * 4 + s2], Vb[s2], o[mt]);
;             SBAR();
; #pragma unroll
;             for (int e = 0; e < 8; ++e) fa[e] = LDF(32768 + 8192 + e * 1024);
;             SBAR();
; #pragma unroll
;             for (int t = 0; t < 4; ++t)
; #pragma unroll
;                 for (int r = 0; r < 16; ++r) S[t][r] *= eg;
; #pragma unroll
;             for (int s2 = 0; s2 < 4; ++s2)
; #pragma unroll
;                 for (int t = 0; t < 2; ++t) S[t] = MFMA32(fb[t * 4 + s2], Vb[s2], S[t]);
;             SBAR();
; #pragma unroll
;             for (int s2 = 0; s2 < 4; ++s2)
; #pragma unroll
;                 for (int t = 2; t < 4; ++t) S[t] = MFMA32(fa[(t - 2) * 4 + s2], Vb[s2], S[t]);
;     ...
;             LAS bf16_t* ost = (LAS bf16_t*)(lds + SCAN_OST + (n & 1) * OST_BYTES) + (4 * hf) * OST_PITCH + wave * 32 + (lane & 31);
; #pragma unroll
;             for (int mt = 0; mt < 2; ++mt)
; #pragma unroll
;                 for (int i = 0; i < 4; ++i) { const unsigned w0 = pk2(o[mt][4 * i], o[mt][4 * i + 1]), w1 = pk2(o[mt][4 * i + 2], o[mt][4 * i + 3]);
;                     LAS bf16_t* d = ost + (mt * 32 + 8 * i) * OST_PITCH;
;                     d[0] = (bf16_t)(w0 & 0xffffu); d[OST_PITCH] = (bf16_t)(w0 >> 16); d[2 * OST_PITCH] = (bf16_t)(w1 & 0xffffu); d[3 * OST_PITCH] = (bf16_t)(w1 >> 16); }
;             LDSBAR();
;         }
;         __builtin_amdgcn_s_setprio(0);
	v_mfma_f32_32x32x16_bf16 v[112:127], v[160:163], v[32:35], v[112:127]
	v_cvt_pk_bf16_f32 v38, v44, v45
	v_cvt_pk_bf16_f32 v39, v46, v47
	s_waitcnt lgkmcnt(11)
	v_mfma_f32_32x32x16_bf16 v[96:111], v[172:175], v[32:35], v[96:111]
	s_waitcnt lgkmcnt(9)
	v_mfma_f32_32x32x16_bf16 v[112:127], v[180:183], v[36:39], v[112:127]
	s_waitcnt lgkmcnt(8)
	v_mfma_f32_32x32x16_bf16 v[96:111], v[184:187], v[36:39], v[96:111]
	v_mfma_f32_32x32x16_bf16 v[80:95], v[164:167], v[32:35], v[80:95]
	v_add_u32_e32 v40, 0x13800, v150
	v_add_u32_e32 v140, 0x15800, v150
	v_add_u32_e32 v148, 0x11c00, v150
	v_add_u32_e32 v151, 0x15c00, v150
	v_mfma_f32_32x32x16_bf16 v[64:79], v[156:159], v[32:35], v[64:79]
	v_add_u32_e32 v32, 0x11800, v150
	ds_read_b128 v[32:35], v32
	ds_read_b128 v[40:43], v40
	ds_read_b128 v[44:47], v150 offset:63488
	ds_read_b128 v[52:55], v150 offset:64512
	ds_read_b128 v[140:143], v140
	ds_read_b128 v[156:159], v148
	v_add_u32_e32 v148, 0x13c00, v150
	ds_read_b128 v[160:163], v148
	ds_read_b128 v[164:167], v151
	v_mfma_f32_32x32x16_bf16 v[80:95], v[168:171], v[36:39], v[80:95]
	v_mfma_f32_32x32x16_bf16 v[64:79], v[176:179], v[36:39], v[64:79]
	v_cvt_pk_bf16_f32 v16, v16, v17
	v_cvt_pk_bf16_f32 v17, v18, v19
	v_cvt_pk_bf16_f32 v18, v20, v21
	v_cvt_pk_bf16_f32 v19, v22, v23
	v_cvt_pk_bf16_f32 v20, v24, v25
	v_cvt_pk_bf16_f32 v21, v26, v27
	s_waitcnt lgkmcnt(14)
	v_mfma_f32_32x32x16_bf16 v[112:127], v[56:59], v[16:19], v[112:127]
	v_cvt_pk_bf16_f32 v22, v28, v29
	v_cvt_pk_bf16_f32 v23, v30, v31
	s_waitcnt lgkmcnt(11)
	v_mfma_f32_32x32x16_bf16 v[96:111], v[132:135], v[16:19], v[96:111]
	s_waitcnt lgkmcnt(9)
	v_mfma_f32_32x32x16_bf16 v[112:127], v[144:147], v[20:23], v[112:127]
	s_waitcnt lgkmcnt(8)
	v_mfma_f32_32x32x16_bf16 v[96:111], v[152:155], v[20:23], v[96:111]
	v_mfma_f32_32x32x16_bf16 v[80:95], v[60:63], v[16:19], v[80:95]
	v_add_u32_e32 v24, 0x1a000, v150
	v_add_u32_e32 v25, 0x1a400, v150
	v_add_u32_e32 v28, 0x1a800, v150
	v_add_u32_e32 v36, 0x1ac00, v150
	v_add_u32_e32 v56, 0x1b400, v150
	v_add_u32_e32 v60, 0x1b800, v150
	v_mfma_f32_32x32x16_bf16 v[64:79], v[48:51], v[16:19], v[64:79]
	v_add_u32_e32 v48, 0x1b000, v150
	ds_read_b128 v[16:19], v24
	ds_read_b128 v[24:27], v25
	ds_read_b128 v[28:31], v28
	ds_read_b128 v[36:39], v36
	ds_read_b128 v[48:51], v48
	ds_read_b128 v[56:59], v56
	v_mfma_f32_32x32x16_bf16 v[80:95], v[128:131], v[20:23], v[80:95]
	v_add_u32_e32 v128, 0x1bc00, v150
	ds_read_b128 v[60:63], v60
	ds_read_b128 v[128:131], v128
	v_mfma_f32_32x32x16_bf16 v[64:79], v[136:139], v[20:23], v[64:79]
	v_cvt_pk_bf16_f32 v0, v0, v1
	v_cvt_pk_bf16_f32 v1, v2, v3
	v_cvt_pk_bf16_f32 v2, v4, v5
	v_cvt_pk_bf16_f32 v3, v6, v7
	v_cvt_pk_bf16_f32 v4, v8, v9
	v_cvt_pk_bf16_f32 v5, v10, v11
	s_waitcnt lgkmcnt(14)
	v_mfma_f32_32x32x16_bf16 v[64:79], v[32:35], v[0:3], v[64:79]
	v_cvt_pk_bf16_f32 v6, v12, v13
	v_cvt_pk_bf16_f32 v7, v14, v15
	v_mfma_f32_32x32x16_bf16 v[112:127], v[40:43], v[0:3], v[112:127]
	s_waitcnt lgkmcnt(11)
	v_mfma_f32_32x32x16_bf16 v[96:111], v[140:143], v[0:3], v[96:111]
	s_waitcnt lgkmcnt(10)
	v_mfma_f32_32x32x16_bf16 v[64:79], v[156:159], v[4:7], v[64:79]
	s_waitcnt lgkmcnt(9)
	v_mfma_f32_32x32x16_bf16 v[112:127], v[160:163], v[4:7], v[112:127]
	s_waitcnt lgkmcnt(8)
	v_mfma_f32_32x32x16_bf16 v[96:111], v[164:167], v[4:7], v[96:111]
	v_mfma_f32_32x32x16_bf16 v[80:95], v[44:47], v[0:3], v[80:95]
	v_mfma_f32_32x32x16_bf16 v[80:95], v[52:55], v[4:7], v[80:95]
	s_nop 11
	v_cvt_pk_bf16_f32 v0, v80, v81
	v_cvt_pk_bf16_f32 v1, v82, v83
	v_cvt_pk_bf16_f32 v2, v84, v85
	v_cvt_pk_bf16_f32 v3, v86, v87
	s_waitcnt lgkmcnt(7)
	s_nop 0
	v_mfma_f32_32x32x16_bf16 v[112:127], v[16:19], v[0:3], v[112:127]
	s_waitcnt lgkmcnt(3)
	v_mfma_f32_32x32x16_bf16 v[96:111], v[48:51], v[0:3], v[96:111]
	v_cvt_pk_bf16_f32 v0, v88, v89
	v_cvt_pk_bf16_f32 v1, v90, v91
	v_cvt_pk_bf16_f32 v2, v92, v93
	v_cvt_pk_bf16_f32 v3, v94, v95
	s_nop 1
	v_mfma_f32_32x32x16_bf16 v[112:127], v[24:27], v[0:3], v[112:127]
	s_waitcnt lgkmcnt(2)
	v_mfma_f32_32x32x16_bf16 v[96:111], v[56:59], v[0:3], v[96:111]
	v_cvt_pk_bf16_f32 v0, v64, v65
	v_cvt_pk_bf16_f32 v1, v66, v67
	v_cvt_pk_bf16_f32 v2, v68, v69
	v_cvt_pk_bf16_f32 v3, v70, v71
	s_nop 1
	v_mfma_f32_32x32x16_bf16 v[112:127], v[28:31], v[0:3], v[112:127]
	s_waitcnt lgkmcnt(1)
	v_mfma_f32_32x32x16_bf16 v[96:111], v[60:63], v[0:3], v[96:111]
	v_cvt_pk_bf16_f32 v0, v72, v73
	v_cvt_pk_bf16_f32 v1, v74, v75
	v_cvt_pk_bf16_f32 v2, v76, v77
	v_cvt_pk_bf16_f32 v3, v78, v79
	s_nop 1
	v_mfma_f32_32x32x16_bf16 v[112:127], v[36:39], v[0:3], v[112:127]
	s_waitcnt lgkmcnt(0)
	v_mfma_f32_32x32x16_bf16 v[96:111], v[128:131], v[0:3], v[96:111]
	s_nop 9
	v_cvt_pk_bf16_f32 v0, v112, v113
	v_cvt_pk_bf16_f32 v1, v114, v115
	ds_write_b16 v149, v0 offset:17408
	ds_write_b16_d16_hi v149, v0 offset:17680
	ds_write_b16 v149, v1 offset:17952
	ds_write_b16_d16_hi v149, v1 offset:18224
	v_cvt_pk_bf16_f32 v0, v116, v117
	v_cvt_pk_bf16_f32 v1, v118, v119
	ds_write_b16 v149, v0 offset:19584
	ds_write_b16_d16_hi v149, v0 offset:19856
	ds_write_b16 v149, v1 offset:20128
	ds_write_b16_d16_hi v149, v1 offset:20400
	v_cvt_pk_bf16_f32 v0, v120, v121
	v_cvt_pk_bf16_f32 v1, v122, v123
	ds_write_b16 v149, v0 offset:21760
	ds_write_b16_d16_hi v149, v0 offset:22032
	ds_write_b16 v149, v1 offset:22304
	ds_write_b16_d16_hi v149, v1 offset:22576
	v_cvt_pk_bf16_f32 v0, v124, v125
	v_cvt_pk_bf16_f32 v1, v126, v127
	ds_write_b16 v149, v0 offset:23936
	ds_write_b16_d16_hi v149, v0 offset:24208
	ds_write_b16 v149, v1 offset:24480
	ds_write_b16_d16_hi v149, v1 offset:24752
	v_cvt_pk_bf16_f32 v0, v96, v97
	v_cvt_pk_bf16_f32 v1, v98, v99
	ds_write_b16 v149, v0 offset:26112
	ds_write_b16_d16_hi v149, v0 offset:26384
	ds_write_b16 v149, v1 offset:26656
	ds_write_b16_d16_hi v149, v1 offset:26928
	v_cvt_pk_bf16_f32 v0, v100, v101
	v_cvt_pk_bf16_f32 v1, v102, v103
	ds_write_b16 v149, v0 offset:28288
	ds_write_b16_d16_hi v149, v0 offset:28560
	ds_write_b16 v149, v1 offset:28832
	ds_write_b16_d16_hi v149, v1 offset:29104
	v_cvt_pk_bf16_f32 v0, v104, v105
	v_cvt_pk_bf16_f32 v1, v106, v107
	ds_write_b16 v149, v0 offset:30464
	ds_write_b16_d16_hi v149, v0 offset:30736
	ds_write_b16 v149, v1 offset:31008
	ds_write_b16_d16_hi v149, v1 offset:31280
	v_cvt_pk_bf16_f32 v0, v108, v109
	v_cvt_pk_bf16_f32 v1, v110, v111
	ds_write_b16 v149, v0 offset:32640
	ds_write_b16_d16_hi v149, v0 offset:32912
	ds_write_b16 v149, v1 offset:33184
	ds_write_b16_d16_hi v149, v1 offset:33456
	s_waitcnt lgkmcnt(0)
	s_barrier
	s_setprio 0
	v_mov_b64_e32 v[250:251], v[206:207]
	s_waitcnt vmcnt(0)
	v_mov_b64_e32 v[210:211], 0x800
	v_mov_b64_e32 v[212:213], 0x7ff
	v_mov_b32_e32 v214, 0x3f317218
	v_mov_b64_e32 v[216:217], 0x700
	v_mov_b64_e32 v[218:219], 0x6ff
	v_mov_b32_e32 v240, 0x358637bd
	v_mov_b32_e32 v241, 1
	v_mov_b32_e32 v242, 0x41b17218
	v_mov_b32_e32 v243, 0x3600000
